# out-proj epilogue: rowsq atomics issued before the residual stores (their completion overlaps)
# baseline (speedup 1.0000x reference)
.LBB0_788:
	s_mov_b32 s21, 0x4b800000
	v_readlane_b32 s92, v246, 13
	v_readlane_b32 s86, v246, 3
	v_readlane_b32 s93, v246, 14
	v_readlane_b32 s87, v246, 4
	s_mov_b64 s[12:13], 0xb0000
	s_waitcnt vmcnt(15)
	v_lshlrev_b32_e32 v144, 16, v152
	v_and_b32_e32 v145, 0xffff0000, v152
	v_lshlrev_b32_e32 v146, 16, v153
	v_and_b32_e32 v147, 0xffff0000, v153
	v_pk_add_f32 v[126:127], v[126:127], v[144:145]
	v_pk_add_f32 v[128:129], v[128:129], v[146:147]
	v_lshlrev_b32_e32 v144, 16, v154
	v_and_b32_e32 v145, 0xffff0000, v154
	v_lshlrev_b32_e32 v146, 16, v155
	v_and_b32_e32 v147, 0xffff0000, v155
	v_pk_add_f32 v[122:123], v[122:123], v[144:145]
	v_pk_add_f32 v[124:125], v[124:125], v[146:147]
	v_mul_f32_e32 v144, v127, v127
	v_mul_f32_e32 v145, v129, v129
	v_fmac_f32_e32 v144, v126, v126
	v_fmac_f32_e32 v145, v128, v128
	v_mul_f32_e32 v146, v123, v123
	v_mul_f32_e32 v147, v125, v125
	v_add_f32_e32 v144, v144, v145
	v_fmac_f32_e32 v146, v122, v122
	v_fmac_f32_e32 v147, v124, v124
	v_add_f32_e32 v146, v146, v147
	v_add_f32_e32 v151, v144, v146
	v_cvt_pk_bf16_f32 v126, v126, v127
	v_cvt_pk_bf16_f32 v127, v128, v129
	v_cvt_pk_bf16_f32 v128, v122, v123
	v_cvt_pk_bf16_f32 v129, v124, v125
	s_waitcnt vmcnt(14)
	v_lshlrev_b32_e32 v144, 16, v156
	v_and_b32_e32 v145, 0xffff0000, v156
	v_lshlrev_b32_e32 v146, 16, v157
	v_and_b32_e32 v147, 0xffff0000, v157
	v_pk_add_f32 v[118:119], v[118:119], v[144:145]
	v_pk_add_f32 v[120:121], v[120:121], v[146:147]
	v_lshlrev_b32_e32 v144, 16, v158
	v_and_b32_e32 v145, 0xffff0000, v158
	v_lshlrev_b32_e32 v146, 16, v159
	v_and_b32_e32 v147, 0xffff0000, v159
	v_pk_add_f32 v[114:115], v[114:115], v[144:145]
	v_pk_add_f32 v[116:117], v[116:117], v[146:147]
	v_mul_f32_e32 v144, v119, v119
	v_mul_f32_e32 v145, v121, v121
	v_fmac_f32_e32 v144, v118, v118
	v_fmac_f32_e32 v145, v120, v120
	v_mul_f32_e32 v146, v115, v115
	v_mul_f32_e32 v147, v117, v117
	v_add_f32_e32 v144, v144, v145
	v_fmac_f32_e32 v146, v114, v114
	v_fmac_f32_e32 v147, v116, v116
	v_add_f32_e32 v146, v146, v147
	v_add_f32_e32 v144, v144, v146
	v_add_f32_e32 v122, v151, v144
	v_cvt_pk_bf16_f32 v118, v118, v119
	v_cvt_pk_bf16_f32 v119, v120, v121
	v_cvt_pk_bf16_f32 v120, v114, v115
	v_cvt_pk_bf16_f32 v121, v116, v117
	s_waitcnt vmcnt(13)
	v_lshlrev_b32_e32 v144, 16, v160
	v_and_b32_e32 v145, 0xffff0000, v160
	v_lshlrev_b32_e32 v146, 16, v161
	v_and_b32_e32 v147, 0xffff0000, v161
	v_pk_add_f32 v[110:111], v[110:111], v[144:145]
	v_pk_add_f32 v[112:113], v[112:113], v[146:147]
	v_lshlrev_b32_e32 v144, 16, v162
	v_and_b32_e32 v145, 0xffff0000, v162
	v_lshlrev_b32_e32 v146, 16, v163
	v_and_b32_e32 v147, 0xffff0000, v163
	v_pk_add_f32 v[106:107], v[106:107], v[144:145]
	v_pk_add_f32 v[108:109], v[108:109], v[146:147]
	v_mul_f32_e32 v144, v111, v111
	v_mul_f32_e32 v145, v113, v113
	v_fmac_f32_e32 v144, v110, v110
	v_fmac_f32_e32 v145, v112, v112
	v_mul_f32_e32 v146, v107, v107
	v_mul_f32_e32 v147, v109, v109
	v_add_f32_e32 v144, v144, v145
	v_fmac_f32_e32 v146, v106, v106
	v_fmac_f32_e32 v147, v108, v108
	v_add_f32_e32 v146, v146, v147
	v_add_f32_e32 v151, v144, v146
	v_cvt_pk_bf16_f32 v110, v110, v111
	v_cvt_pk_bf16_f32 v111, v112, v113
	v_cvt_pk_bf16_f32 v112, v106, v107
	v_cvt_pk_bf16_f32 v113, v108, v109
	s_waitcnt vmcnt(12)
	v_lshlrev_b32_e32 v144, 16, v182
	v_and_b32_e32 v145, 0xffff0000, v182
	v_lshlrev_b32_e32 v146, 16, v183
	v_and_b32_e32 v147, 0xffff0000, v183
	v_pk_add_f32 v[102:103], v[102:103], v[144:145]
	v_pk_add_f32 v[104:105], v[104:105], v[146:147]
	v_lshlrev_b32_e32 v144, 16, v184
	v_and_b32_e32 v145, 0xffff0000, v184
	v_lshlrev_b32_e32 v146, 16, v185
	v_and_b32_e32 v147, 0xffff0000, v185
	v_pk_add_f32 v[98:99], v[98:99], v[144:145]
	v_pk_add_f32 v[100:101], v[100:101], v[146:147]
	v_mul_f32_e32 v144, v103, v103
	v_mul_f32_e32 v145, v105, v105
	v_fmac_f32_e32 v144, v102, v102
	v_fmac_f32_e32 v145, v104, v104
	v_mul_f32_e32 v146, v99, v99
	v_mul_f32_e32 v147, v101, v101
	v_add_f32_e32 v144, v144, v145
	v_fmac_f32_e32 v146, v98, v98
	v_fmac_f32_e32 v147, v100, v100
	v_add_f32_e32 v146, v146, v147
	v_add_f32_e32 v144, v144, v146
	v_add_f32_e32 v106, v151, v144
	v_cvt_pk_bf16_f32 v102, v102, v103
	v_cvt_pk_bf16_f32 v103, v104, v105
	v_cvt_pk_bf16_f32 v104, v98, v99
	v_cvt_pk_bf16_f32 v105, v100, v101
	s_waitcnt vmcnt(11)
	v_lshlrev_b32_e32 v144, 16, v186
	v_and_b32_e32 v145, 0xffff0000, v186
	v_lshlrev_b32_e32 v146, 16, v187
	v_and_b32_e32 v147, 0xffff0000, v187
	v_pk_add_f32 v[94:95], v[94:95], v[144:145]
	v_pk_add_f32 v[96:97], v[96:97], v[146:147]
	v_lshlrev_b32_e32 v144, 16, v188
	v_and_b32_e32 v145, 0xffff0000, v188
	v_lshlrev_b32_e32 v146, 16, v189
	v_and_b32_e32 v147, 0xffff0000, v189
	v_pk_add_f32 v[90:91], v[90:91], v[144:145]
	v_pk_add_f32 v[92:93], v[92:93], v[146:147]
	v_mul_f32_e32 v144, v95, v95
	v_mul_f32_e32 v145, v97, v97
	v_fmac_f32_e32 v144, v94, v94
	v_fmac_f32_e32 v145, v96, v96
	v_mul_f32_e32 v146, v91, v91
	v_mul_f32_e32 v147, v93, v93
	v_add_f32_e32 v144, v144, v145
	v_fmac_f32_e32 v146, v90, v90
	v_fmac_f32_e32 v147, v92, v92
	v_add_f32_e32 v146, v146, v147
	v_add_f32_e32 v151, v144, v146
	v_cvt_pk_bf16_f32 v94, v94, v95
	v_cvt_pk_bf16_f32 v95, v96, v97
	v_cvt_pk_bf16_f32 v96, v90, v91
	v_cvt_pk_bf16_f32 v97, v92, v93
	s_waitcnt vmcnt(10)
	v_lshlrev_b32_e32 v144, 16, v190
	v_and_b32_e32 v145, 0xffff0000, v190
	v_lshlrev_b32_e32 v146, 16, v191
	v_and_b32_e32 v147, 0xffff0000, v191
	v_pk_add_f32 v[86:87], v[86:87], v[144:145]
	v_pk_add_f32 v[88:89], v[88:89], v[146:147]
	v_lshlrev_b32_e32 v144, 16, v192
	v_and_b32_e32 v145, 0xffff0000, v192
	v_lshlrev_b32_e32 v146, 16, v193
	v_and_b32_e32 v147, 0xffff0000, v193
	v_pk_add_f32 v[82:83], v[82:83], v[144:145]
	v_pk_add_f32 v[84:85], v[84:85], v[146:147]
	v_mul_f32_e32 v144, v87, v87
	v_mul_f32_e32 v145, v89, v89
	v_fmac_f32_e32 v144, v86, v86
	v_fmac_f32_e32 v145, v88, v88
	v_mul_f32_e32 v146, v83, v83
	v_mul_f32_e32 v147, v85, v85
	v_add_f32_e32 v144, v144, v145
	v_fmac_f32_e32 v146, v82, v82
	v_fmac_f32_e32 v147, v84, v84
	v_add_f32_e32 v146, v146, v147
	v_add_f32_e32 v144, v144, v146
	v_add_f32_e32 v90, v151, v144
	v_cvt_pk_bf16_f32 v86, v86, v87
	v_cvt_pk_bf16_f32 v87, v88, v89
	v_cvt_pk_bf16_f32 v88, v82, v83
	v_cvt_pk_bf16_f32 v89, v84, v85
	s_waitcnt vmcnt(9)
	v_lshlrev_b32_e32 v144, 16, v194
	v_and_b32_e32 v145, 0xffff0000, v194
	v_lshlrev_b32_e32 v146, 16, v195
	v_and_b32_e32 v147, 0xffff0000, v195
	v_pk_add_f32 v[78:79], v[78:79], v[144:145]
	v_pk_add_f32 v[80:81], v[80:81], v[146:147]
	v_lshlrev_b32_e32 v144, 16, v196
	v_and_b32_e32 v145, 0xffff0000, v196
	v_lshlrev_b32_e32 v146, 16, v197
	v_and_b32_e32 v147, 0xffff0000, v197
	v_pk_add_f32 v[74:75], v[74:75], v[144:145]
	v_pk_add_f32 v[76:77], v[76:77], v[146:147]
	v_mul_f32_e32 v144, v79, v79
	v_mul_f32_e32 v145, v81, v81
	v_fmac_f32_e32 v144, v78, v78
	v_fmac_f32_e32 v145, v80, v80
	v_mul_f32_e32 v146, v75, v75
	v_mul_f32_e32 v147, v77, v77
	v_add_f32_e32 v144, v144, v145
	v_fmac_f32_e32 v146, v74, v74
	v_fmac_f32_e32 v147, v76, v76
	v_add_f32_e32 v146, v146, v147
	v_add_f32_e32 v151, v144, v146
	v_cvt_pk_bf16_f32 v78, v78, v79
	v_cvt_pk_bf16_f32 v79, v80, v81
	v_cvt_pk_bf16_f32 v80, v74, v75
	v_cvt_pk_bf16_f32 v81, v76, v77
	s_waitcnt vmcnt(8)
	v_lshlrev_b32_e32 v144, 16, v198
	v_and_b32_e32 v145, 0xffff0000, v198
	v_lshlrev_b32_e32 v146, 16, v199
	v_and_b32_e32 v147, 0xffff0000, v199
	v_pk_add_f32 v[70:71], v[70:71], v[144:145]
	v_pk_add_f32 v[72:73], v[72:73], v[146:147]
	v_lshlrev_b32_e32 v144, 16, v200
	v_and_b32_e32 v145, 0xffff0000, v200
	v_lshlrev_b32_e32 v146, 16, v201
	v_and_b32_e32 v147, 0xffff0000, v201
	v_pk_add_f32 v[66:67], v[66:67], v[144:145]
	v_pk_add_f32 v[68:69], v[68:69], v[146:147]
	v_mul_f32_e32 v144, v71, v71
	v_mul_f32_e32 v145, v73, v73
	v_fmac_f32_e32 v144, v70, v70
	v_fmac_f32_e32 v145, v72, v72
	v_mul_f32_e32 v146, v67, v67
	v_mul_f32_e32 v147, v69, v69
	v_add_f32_e32 v144, v144, v145
	v_fmac_f32_e32 v146, v66, v66
	v_fmac_f32_e32 v147, v68, v68
	v_add_f32_e32 v146, v146, v147
	v_add_f32_e32 v144, v144, v146
	v_add_f32_e32 v74, v151, v144
	v_cvt_pk_bf16_f32 v70, v70, v71
	v_cvt_pk_bf16_f32 v71, v72, v73
	v_cvt_pk_bf16_f32 v72, v66, v67
	v_cvt_pk_bf16_f32 v73, v68, v69
	s_waitcnt vmcnt(7)
	v_lshlrev_b32_e32 v144, 16, v202
	v_and_b32_e32 v145, 0xffff0000, v202
	v_lshlrev_b32_e32 v146, 16, v203
	v_and_b32_e32 v147, 0xffff0000, v203
	v_pk_add_f32 v[62:63], v[62:63], v[144:145]
	v_pk_add_f32 v[64:65], v[64:65], v[146:147]
	v_lshlrev_b32_e32 v144, 16, v204
	v_and_b32_e32 v145, 0xffff0000, v204
	v_lshlrev_b32_e32 v146, 16, v205
	v_and_b32_e32 v147, 0xffff0000, v205
	v_pk_add_f32 v[58:59], v[58:59], v[144:145]
	v_pk_add_f32 v[60:61], v[60:61], v[146:147]
	v_mul_f32_e32 v144, v63, v63
	v_mul_f32_e32 v145, v65, v65
	v_fmac_f32_e32 v144, v62, v62
	v_fmac_f32_e32 v145, v64, v64
	v_mul_f32_e32 v146, v59, v59
	v_mul_f32_e32 v147, v61, v61
	v_add_f32_e32 v144, v144, v145
	v_fmac_f32_e32 v146, v58, v58
	v_fmac_f32_e32 v147, v60, v60
	v_add_f32_e32 v146, v146, v147
	v_add_f32_e32 v151, v144, v146
	v_cvt_pk_bf16_f32 v62, v62, v63
	v_cvt_pk_bf16_f32 v63, v64, v65
	v_cvt_pk_bf16_f32 v64, v58, v59
	v_cvt_pk_bf16_f32 v65, v60, v61
	s_waitcnt vmcnt(6)
	v_lshlrev_b32_e32 v144, 16, v206
	v_and_b32_e32 v145, 0xffff0000, v206
	v_lshlrev_b32_e32 v146, 16, v207
	v_and_b32_e32 v147, 0xffff0000, v207
	v_pk_add_f32 v[54:55], v[54:55], v[144:145]
	v_pk_add_f32 v[56:57], v[56:57], v[146:147]
	v_lshlrev_b32_e32 v144, 16, v208
	v_and_b32_e32 v145, 0xffff0000, v208
	v_lshlrev_b32_e32 v146, 16, v209
	v_and_b32_e32 v147, 0xffff0000, v209
	v_pk_add_f32 v[50:51], v[50:51], v[144:145]
	v_pk_add_f32 v[52:53], v[52:53], v[146:147]
	v_mul_f32_e32 v144, v55, v55
	v_mul_f32_e32 v145, v57, v57
	v_fmac_f32_e32 v144, v54, v54
	v_fmac_f32_e32 v145, v56, v56
	v_mul_f32_e32 v146, v51, v51
	v_mul_f32_e32 v147, v53, v53
	v_add_f32_e32 v144, v144, v145
	v_fmac_f32_e32 v146, v50, v50
	v_fmac_f32_e32 v147, v52, v52
	v_add_f32_e32 v146, v146, v147
	v_add_f32_e32 v144, v144, v146
	v_add_f32_e32 v58, v151, v144
	v_cvt_pk_bf16_f32 v54, v54, v55
	v_cvt_pk_bf16_f32 v55, v56, v57
	v_cvt_pk_bf16_f32 v56, v50, v51
	v_cvt_pk_bf16_f32 v57, v52, v53
	s_waitcnt vmcnt(5)
	v_lshlrev_b32_e32 v144, 16, v222
	v_and_b32_e32 v145, 0xffff0000, v222
	v_lshlrev_b32_e32 v146, 16, v223
	v_and_b32_e32 v147, 0xffff0000, v223
	v_pk_add_f32 v[46:47], v[46:47], v[144:145]
	v_pk_add_f32 v[48:49], v[48:49], v[146:147]
	v_lshlrev_b32_e32 v144, 16, v224
	v_and_b32_e32 v145, 0xffff0000, v224
	v_lshlrev_b32_e32 v146, 16, v225
	v_and_b32_e32 v147, 0xffff0000, v225
	v_pk_add_f32 v[42:43], v[42:43], v[144:145]
	v_pk_add_f32 v[44:45], v[44:45], v[146:147]
	v_mul_f32_e32 v144, v47, v47
	v_mul_f32_e32 v145, v49, v49
	v_fmac_f32_e32 v144, v46, v46
	v_fmac_f32_e32 v145, v48, v48
	v_mul_f32_e32 v146, v43, v43
	v_mul_f32_e32 v147, v45, v45
	v_add_f32_e32 v144, v144, v145
	v_fmac_f32_e32 v146, v42, v42
	v_fmac_f32_e32 v147, v44, v44
	v_add_f32_e32 v146, v146, v147
	v_add_f32_e32 v151, v144, v146
	v_cvt_pk_bf16_f32 v46, v46, v47
	v_cvt_pk_bf16_f32 v47, v48, v49
	v_cvt_pk_bf16_f32 v48, v42, v43
	v_cvt_pk_bf16_f32 v49, v44, v45
	s_waitcnt vmcnt(4)
	v_lshlrev_b32_e32 v144, 16, v226
	v_and_b32_e32 v145, 0xffff0000, v226
	v_lshlrev_b32_e32 v146, 16, v227
	v_and_b32_e32 v147, 0xffff0000, v227
	v_pk_add_f32 v[38:39], v[38:39], v[144:145]
	v_pk_add_f32 v[40:41], v[40:41], v[146:147]
	v_lshlrev_b32_e32 v144, 16, v228
	v_and_b32_e32 v145, 0xffff0000, v228
	v_lshlrev_b32_e32 v146, 16, v229
	v_and_b32_e32 v147, 0xffff0000, v229
	v_pk_add_f32 v[34:35], v[34:35], v[144:145]
	v_pk_add_f32 v[36:37], v[36:37], v[146:147]
	v_mul_f32_e32 v144, v39, v39
	v_mul_f32_e32 v145, v41, v41
	v_fmac_f32_e32 v144, v38, v38
	v_fmac_f32_e32 v145, v40, v40
	v_mul_f32_e32 v146, v35, v35
	v_mul_f32_e32 v147, v37, v37
	v_add_f32_e32 v144, v144, v145
	v_fmac_f32_e32 v146, v34, v34
	v_fmac_f32_e32 v147, v36, v36
	v_add_f32_e32 v146, v146, v147
	v_add_f32_e32 v144, v144, v146
	v_add_f32_e32 v42, v151, v144
	v_cvt_pk_bf16_f32 v38, v38, v39
	v_cvt_pk_bf16_f32 v39, v40, v41
	v_cvt_pk_bf16_f32 v40, v34, v35
	v_cvt_pk_bf16_f32 v41, v36, v37
	s_waitcnt vmcnt(3)
	v_lshlrev_b32_e32 v144, 16, v230
	v_and_b32_e32 v145, 0xffff0000, v230
	v_lshlrev_b32_e32 v146, 16, v231
	v_and_b32_e32 v147, 0xffff0000, v231
	v_pk_add_f32 v[30:31], v[30:31], v[144:145]
	v_pk_add_f32 v[32:33], v[32:33], v[146:147]
	v_lshlrev_b32_e32 v144, 16, v232
	v_and_b32_e32 v145, 0xffff0000, v232
	v_lshlrev_b32_e32 v146, 16, v233
	v_and_b32_e32 v147, 0xffff0000, v233
	v_pk_add_f32 v[26:27], v[26:27], v[144:145]
	v_pk_add_f32 v[28:29], v[28:29], v[146:147]
	v_mul_f32_e32 v144, v31, v31
	v_mul_f32_e32 v145, v33, v33
	v_fmac_f32_e32 v144, v30, v30
	v_fmac_f32_e32 v145, v32, v32
	v_mul_f32_e32 v146, v27, v27
	v_mul_f32_e32 v147, v29, v29
	v_add_f32_e32 v144, v144, v145
	v_fmac_f32_e32 v146, v26, v26
	v_fmac_f32_e32 v147, v28, v28
	v_add_f32_e32 v146, v146, v147
	v_add_f32_e32 v151, v144, v146
	v_cvt_pk_bf16_f32 v30, v30, v31
	v_cvt_pk_bf16_f32 v31, v32, v33
	v_cvt_pk_bf16_f32 v32, v26, v27
	v_cvt_pk_bf16_f32 v33, v28, v29
	s_waitcnt vmcnt(2)
	v_lshlrev_b32_e32 v144, 16, v234
	v_and_b32_e32 v145, 0xffff0000, v234
	v_lshlrev_b32_e32 v146, 16, v235
	v_and_b32_e32 v147, 0xffff0000, v235
	v_pk_add_f32 v[22:23], v[22:23], v[144:145]
	v_pk_add_f32 v[24:25], v[24:25], v[146:147]
	v_lshlrev_b32_e32 v144, 16, v236
	v_and_b32_e32 v145, 0xffff0000, v236
	v_lshlrev_b32_e32 v146, 16, v237
	v_and_b32_e32 v147, 0xffff0000, v237
	v_pk_add_f32 v[18:19], v[18:19], v[144:145]
	v_pk_add_f32 v[20:21], v[20:21], v[146:147]
	v_mul_f32_e32 v144, v23, v23
	v_mul_f32_e32 v145, v25, v25
	v_fmac_f32_e32 v144, v22, v22
	v_fmac_f32_e32 v145, v24, v24
	v_mul_f32_e32 v146, v19, v19
	v_mul_f32_e32 v147, v21, v21
	v_add_f32_e32 v144, v144, v145
	v_fmac_f32_e32 v146, v18, v18
	v_fmac_f32_e32 v147, v20, v20
	v_add_f32_e32 v146, v146, v147
	v_add_f32_e32 v144, v144, v146
	v_add_f32_e32 v26, v151, v144
	v_cvt_pk_bf16_f32 v22, v22, v23
	v_cvt_pk_bf16_f32 v23, v24, v25
	v_cvt_pk_bf16_f32 v24, v18, v19
	v_cvt_pk_bf16_f32 v25, v20, v21
	s_waitcnt vmcnt(1)
	v_lshlrev_b32_e32 v144, 16, v238
	v_and_b32_e32 v145, 0xffff0000, v238
	v_lshlrev_b32_e32 v146, 16, v239
	v_and_b32_e32 v147, 0xffff0000, v239
	v_pk_add_f32 v[14:15], v[14:15], v[144:145]
	v_pk_add_f32 v[16:17], v[16:17], v[146:147]
	v_lshlrev_b32_e32 v144, 16, v240
	v_and_b32_e32 v145, 0xffff0000, v240
	v_lshlrev_b32_e32 v146, 16, v241
	v_and_b32_e32 v147, 0xffff0000, v241
	v_pk_add_f32 v[10:11], v[10:11], v[144:145]
	v_pk_add_f32 v[12:13], v[12:13], v[146:147]
	v_mul_f32_e32 v144, v15, v15
	v_mul_f32_e32 v145, v17, v17
	v_fmac_f32_e32 v144, v14, v14
	v_fmac_f32_e32 v145, v16, v16
	v_mul_f32_e32 v146, v11, v11
	v_mul_f32_e32 v147, v13, v13
	v_add_f32_e32 v144, v144, v145
	v_fmac_f32_e32 v146, v10, v10
	v_fmac_f32_e32 v147, v12, v12
	v_add_f32_e32 v146, v146, v147
	v_add_f32_e32 v151, v144, v146
	v_cvt_pk_bf16_f32 v14, v14, v15
	v_cvt_pk_bf16_f32 v15, v16, v17
	v_cvt_pk_bf16_f32 v16, v10, v11
	v_cvt_pk_bf16_f32 v17, v12, v13
	s_waitcnt vmcnt(0)
	v_lshlrev_b32_e32 v144, 16, v242
	v_and_b32_e32 v145, 0xffff0000, v242
	v_lshlrev_b32_e32 v146, 16, v243
	v_and_b32_e32 v147, 0xffff0000, v243
	v_pk_add_f32 v[6:7], v[6:7], v[144:145]
	v_pk_add_f32 v[8:9], v[8:9], v[146:147]
	v_lshlrev_b32_e32 v144, 16, v244
	v_and_b32_e32 v145, 0xffff0000, v244
	v_lshlrev_b32_e32 v146, 16, v245
	v_and_b32_e32 v147, 0xffff0000, v245
	v_pk_add_f32 v[2:3], v[2:3], v[144:145]
	v_pk_add_f32 v[4:5], v[4:5], v[146:147]
	v_mul_f32_e32 v144, v7, v7
	v_mul_f32_e32 v145, v9, v9
	v_fmac_f32_e32 v144, v6, v6
	v_fmac_f32_e32 v145, v8, v8
	v_mul_f32_e32 v146, v3, v3
	v_mul_f32_e32 v147, v5, v5
	v_add_f32_e32 v144, v144, v145
	v_fmac_f32_e32 v146, v2, v2
	v_fmac_f32_e32 v147, v4, v4
	v_add_f32_e32 v146, v146, v147
	v_add_f32_e32 v144, v144, v146
	v_add_f32_e32 v10, v151, v144
	v_cvt_pk_bf16_f32 v6, v6, v7
	v_cvt_pk_bf16_f32 v7, v8, v9
	v_cvt_pk_bf16_f32 v8, v2, v3
	v_cvt_pk_bf16_f32 v9, v4, v5
	v_and_b32_e32 v115, 64, v217
	v_xor_b32_e32 v114, 16, v217
	v_add_u32_e32 v115, 64, v115
	v_cmp_lt_i32_e32 vcc, v114, v115
	s_nop 1
	v_cndmask_b32_e32 v114, v217, v114, vcc
	v_lshlrev_b32_e32 v116, 2, v114
	v_xor_b32_e32 v114, 32, v217
	v_cmp_lt_i32_e32 vcc, v114, v115
	s_nop 1
	v_cndmask_b32_e32 v114, v217, v114, vcc
	v_lshlrev_b32_e32 v117, 2, v114
	ds_bpermute_b32 v123, v116, v122
	ds_bpermute_b32 v107, v116, v106
	ds_bpermute_b32 v91, v116, v90
	ds_bpermute_b32 v75, v116, v74
	ds_bpermute_b32 v59, v116, v58
	ds_bpermute_b32 v43, v116, v42
	ds_bpermute_b32 v27, v116, v26
	ds_bpermute_b32 v11, v116, v10
	s_waitcnt lgkmcnt(7)
	v_add_f32_e32 v122, v122, v123
	s_waitcnt lgkmcnt(6)
	v_add_f32_e32 v106, v106, v107
	s_waitcnt lgkmcnt(5)
	v_add_f32_e32 v90, v90, v91
	s_waitcnt lgkmcnt(4)
	v_add_f32_e32 v74, v74, v75
	s_waitcnt lgkmcnt(3)
	v_add_f32_e32 v58, v58, v59
	s_waitcnt lgkmcnt(2)
	v_add_f32_e32 v42, v42, v43
	s_waitcnt lgkmcnt(1)
	v_add_f32_e32 v26, v26, v27
	s_waitcnt lgkmcnt(0)
	v_add_f32_e32 v10, v10, v11
	ds_bpermute_b32 v123, v117, v122
	ds_bpermute_b32 v107, v117, v106
	ds_bpermute_b32 v91, v117, v90
	ds_bpermute_b32 v75, v117, v74
	ds_bpermute_b32 v59, v117, v58
	ds_bpermute_b32 v43, v117, v42
	ds_bpermute_b32 v27, v117, v26
	ds_bpermute_b32 v11, v117, v10
	s_and_saveexec_b64 s[50:51], s[36:37]
	s_waitcnt lgkmcnt(7)
	v_add_f32_e32 v122, v122, v123
	v_fma_f32 v122, v122, s21, 0.5
	v_trunc_f32_e32 v122, v122
	v_mul_f32_e32 v123, 0x2f800000, v122
	v_floor_f32_e32 v123, v123
	v_fmac_f32_e32 v122, 0xcf800000, v123
	v_cvt_u32_f32_e32 v122, v122
	v_cvt_u32_f32_e32 v123, v123
	global_atomic_add_x2 v180, v[122:123], s[24:25]
	s_waitcnt lgkmcnt(6)
	v_add_f32_e32 v106, v106, v107
	v_fma_f32 v106, v106, s21, 0.5
	v_trunc_f32_e32 v106, v106
	v_mul_f32_e32 v107, 0x2f800000, v106
	v_floor_f32_e32 v107, v107
	v_fmac_f32_e32 v106, 0xcf800000, v107
	v_cvt_u32_f32_e32 v106, v106
	v_cvt_u32_f32_e32 v107, v107
	global_atomic_add_x2 v180, v[106:107], s[24:25] offset:128
	s_waitcnt lgkmcnt(5)
	v_add_f32_e32 v90, v90, v91
	v_fma_f32 v90, v90, s21, 0.5
	v_trunc_f32_e32 v90, v90
	v_mul_f32_e32 v91, 0x2f800000, v90
	v_floor_f32_e32 v91, v91
	v_fmac_f32_e32 v90, 0xcf800000, v91
	v_cvt_u32_f32_e32 v90, v90
	v_cvt_u32_f32_e32 v91, v91
	global_atomic_add_x2 v180, v[90:91], s[24:25] offset:256
	s_waitcnt lgkmcnt(4)
	v_add_f32_e32 v74, v74, v75
	v_fma_f32 v74, v74, s21, 0.5
	v_trunc_f32_e32 v74, v74
	v_mul_f32_e32 v75, 0x2f800000, v74
	v_floor_f32_e32 v75, v75
	v_fmac_f32_e32 v74, 0xcf800000, v75
	v_cvt_u32_f32_e32 v74, v74
	v_cvt_u32_f32_e32 v75, v75
	global_atomic_add_x2 v180, v[74:75], s[24:25] offset:384
	s_waitcnt lgkmcnt(3)
	v_add_f32_e32 v58, v58, v59
	v_fma_f32 v58, v58, s21, 0.5
	v_trunc_f32_e32 v58, v58
	v_mul_f32_e32 v59, 0x2f800000, v58
	v_floor_f32_e32 v59, v59
	v_fmac_f32_e32 v58, 0xcf800000, v59
	v_cvt_u32_f32_e32 v58, v58
	v_cvt_u32_f32_e32 v59, v59
	global_atomic_add_x2 v180, v[58:59], s[24:25] offset:1024
	s_waitcnt lgkmcnt(2)
	v_add_f32_e32 v42, v42, v43
	v_fma_f32 v42, v42, s21, 0.5
	v_trunc_f32_e32 v42, v42
	v_mul_f32_e32 v43, 0x2f800000, v42
	v_floor_f32_e32 v43, v43
	v_fmac_f32_e32 v42, 0xcf800000, v43
	v_cvt_u32_f32_e32 v42, v42
	v_cvt_u32_f32_e32 v43, v43
	global_atomic_add_x2 v180, v[42:43], s[24:25] offset:1152
	s_waitcnt lgkmcnt(1)
	v_add_f32_e32 v26, v26, v27
	v_fma_f32 v26, v26, s21, 0.5
	v_trunc_f32_e32 v26, v26
	v_mul_f32_e32 v27, 0x2f800000, v26
	v_floor_f32_e32 v27, v27
	v_fmac_f32_e32 v26, 0xcf800000, v27
	v_cvt_u32_f32_e32 v26, v26
	v_cvt_u32_f32_e32 v27, v27
	global_atomic_add_x2 v180, v[26:27], s[24:25] offset:1280
	s_waitcnt lgkmcnt(0)
	v_add_f32_e32 v10, v10, v11
	v_fma_f32 v10, v10, s21, 0.5
	v_trunc_f32_e32 v10, v10
	v_mul_f32_e32 v11, 0x2f800000, v10
	v_floor_f32_e32 v11, v11
	v_fmac_f32_e32 v10, 0xcf800000, v11
	v_cvt_u32_f32_e32 v10, v10
	v_cvt_u32_f32_e32 v11, v11
	global_atomic_add_x2 v180, v[10:11], s[24:25] offset:1408
.LBB0_804:
	s_or_b64 exec, exec, s[50:51]
	global_store_dwordx4 v142, v[126:129], s[14:15] sc1
	global_store_dwordx4 v142, v[118:121], s[14:15] offset:256 sc1
	v_add_u32_e32 v143, 0x10000, v142
	global_store_dwordx4 v143, v[110:113], s[14:15] sc1
	global_store_dwordx4 v143, v[102:105], s[14:15] offset:256 sc1
	v_add_u32_e32 v143, 0x20000, v142
	global_store_dwordx4 v143, v[94:97], s[14:15] sc1
	global_store_dwordx4 v143, v[86:89], s[14:15] offset:256 sc1
	v_add_u32_e32 v143, 0x30000, v142
	global_store_dwordx4 v143, v[78:81], s[14:15] sc1
	global_store_dwordx4 v143, v[70:73], s[14:15] offset:256 sc1
	v_add_u32_e32 v143, 0x80000, v142
	global_store_dwordx4 v143, v[62:65], s[14:15] sc1
	global_store_dwordx4 v143, v[54:57], s[14:15] offset:256 sc1
	v_add_u32_e32 v143, 0x90000, v142
	global_store_dwordx4 v143, v[46:49], s[14:15] sc1
	global_store_dwordx4 v143, v[38:41], s[14:15] offset:256 sc1
	v_add_u32_e32 v143, 0xa0000, v142
	global_store_dwordx4 v143, v[30:33], s[14:15] sc1
	global_store_dwordx4 v143, v[22:25], s[14:15] offset:256 sc1
	v_add_u32_e32 v143, 0xb0000, v142
	global_store_dwordx4 v143, v[14:17], s[14:15] sc1
	global_store_dwordx4 v143, v[6:9], s[14:15] offset:256 sc1
	s_andn2_b64 vcc, exec, s[38:39]
	s_mov_b64 s[38:39], -1
	s_cbranch_vccnz .LBB0_777
	s_andn2_b64 vcc, exec, s[6:7]
	s_cbranch_vccnz .LBB0_776
	s_barrier
	s_branch .LBB0_776
